# final RMSNorm output stores made write-through (sc1)
# baseline (speedup 1.0000x reference)
.LBB0_2953:
	s_waitcnt vmcnt(0) lgkmcnt(0)
	v_pk_mul_f32 v[36:37], v[14:15], v[14:15]
	v_pk_mul_f32 v[38:39], v[12:13], v[12:13]
	v_pk_mul_f32 v[32:33], v[10:11], v[10:11]
	v_pk_mul_f32 v[34:35], v[8:9], v[8:9]
	v_pk_mov_b32 v[40:41], v[38:39], v[36:37] op_sel:[1,0]
	v_mov_b32_e32 v39, v37
	v_pk_add_f32 v[36:37], v[40:41], v[38:39]
	v_pk_mov_b32 v[38:39], v[34:35], v[32:33] op_sel:[1,0]
	v_mov_b32_e32 v35, v33
	v_pk_add_f32 v[32:33], v[38:39], v[34:35]
	v_pk_add_f32 v[36:37], v[36:37], v[36:37] op_sel_hi:[0,1]
	v_pk_add_f32 v[38:39], v[32:33], v[32:33] op_sel_hi:[0,1]
	v_mul_f32_e32 v32, v4, v4
	v_pk_fma_f32 v[40:41], v[4:5], v[4:5], v[32:33] op_sel_hi:[1,1,0]
	v_mul_f32_e32 v32, v6, v6
	v_pk_fma_f32 v[42:43], v[6:7], v[6:7], v[32:33] op_sel_hi:[1,1,0]
	flat_load_dwordx4 v[32:35], v[18:19]
	v_mul_f32_e32 v40, v0, v0
	v_mul_f32_e32 v42, v1, v1
	v_mul_f32_e32 v36, v2, v2
	v_mul_f32_e32 v38, v3, v3
	v_pk_add_f32 v[40:41], v[40:41], v[42:43]
	v_pk_add_f32 v[36:37], v[36:37], v[38:39]
	s_add_i32 s56, s56, s58
	v_pk_add_f32 v[36:37], v[40:41], v[36:37]
	s_cmp_lt_i32 s56, 0x8800
	v_add_f32_e32 v36, v36, v37
	ds_bpermute_b32 v37, v24, v36
	s_waitcnt lgkmcnt(0)
	v_add_f32_e32 v36, v36, v37
	ds_bpermute_b32 v37, v25, v36
	s_waitcnt lgkmcnt(0)
	v_add_f32_e32 v36, v36, v37
	ds_bpermute_b32 v37, v26, v36
	s_waitcnt lgkmcnt(0)
	v_add_f32_e32 v36, v36, v37
	ds_bpermute_b32 v37, v27, v36
	s_waitcnt lgkmcnt(0)
	v_add_f32_e32 v36, v36, v37
	ds_bpermute_b32 v37, v28, v36
	s_waitcnt lgkmcnt(0)
	v_add_f32_e32 v36, v36, v37
	ds_bpermute_b32 v37, v29, v36
	s_waitcnt lgkmcnt(0)
	v_add_f32_e32 v36, v36, v37
	v_fmamk_f32 v36, v36, 0x3a800000, v30
	v_mul_f32_e32 v37, 0x4f800000, v36
	v_cmp_gt_f32_e32 vcc, s8, v36
	s_nop 1
	v_cndmask_b32_e32 v36, v36, v37, vcc
	v_sqrt_f32_e32 v37, v36
	s_nop 0
	v_add_u32_e32 v38, -1, v37
	v_add_u32_e32 v39, 1, v37
	v_fma_f32 v40, -v38, v37, v36
	v_fma_f32 v41, -v39, v37, v36
	v_cmp_ge_f32_e64 s[0:1], 0, v40
	s_nop 1
	v_cndmask_b32_e64 v37, v37, v38, s[0:1]
	v_cmp_lt_f32_e64 s[0:1], 0, v41
	s_nop 1
	v_cndmask_b32_e64 v37, v37, v39, s[0:1]
	v_mul_f32_e32 v38, 0x37800000, v37
	v_cndmask_b32_e32 v37, v37, v38, vcc
	v_cmp_class_f32_e32 vcc, v36, v31
	s_nop 1
	v_cndmask_b32_e32 v36, v37, v36, vcc
	v_div_scale_f32 v37, s[0:1], v36, v36, 1.0
	v_rcp_f32_e32 v38, v37
	v_div_scale_f32 v39, vcc, 1.0, v36, 1.0
	v_fma_f32 v40, -v37, v38, 1.0
	v_fmac_f32_e32 v38, v40, v38
	v_mul_f32_e32 v40, v39, v38
	v_fma_f32 v41, -v37, v40, v39
	v_fmac_f32_e32 v40, v41, v38
	v_fma_f32 v37, -v37, v40, v39
	v_div_fmas_f32 v37, v37, v38, v40
	v_div_fixup_f32 v36, v37, v36, 1.0
	v_pk_mul_f32 v[12:13], v[12:13], v[36:37] op_sel_hi:[1,0]
	v_pk_mul_f32 v[14:15], v[14:15], v[36:37] op_sel_hi:[1,0]
	s_waitcnt vmcnt(0)
	v_pk_mul_f32 v[12:13], v[32:33], v[12:13]
	v_pk_mul_f32 v[14:15], v[34:35], v[14:15]
	flat_store_dwordx4 v[22:23], v[12:15] sc1
	flat_load_dwordx4 v[12:15], v[18:19] offset:1024
	v_pk_mul_f32 v[10:11], v[10:11], v[36:37] op_sel_hi:[1,0]
	v_pk_mul_f32 v[8:9], v[8:9], v[36:37] op_sel_hi:[1,0]
	v_pk_mul_f32 v[6:7], v[6:7], v[36:37] op_sel_hi:[1,0]
	v_pk_mul_f32 v[4:5], v[4:5], v[36:37] op_sel_hi:[1,0]
	v_pk_mul_f32 v[2:3], v[2:3], v[36:37] op_sel_hi:[1,0]
	v_pk_mul_f32 v[0:1], v[0:1], v[36:37] op_sel_hi:[1,0]
	s_waitcnt vmcnt(0) lgkmcnt(0)
	v_pk_mul_f32 v[8:9], v[12:13], v[8:9]
	v_pk_mul_f32 v[10:11], v[14:15], v[10:11]
	flat_store_dwordx4 v[22:23], v[8:11] offset:1024 sc1
	flat_load_dwordx4 v[8:11], v[18:19] offset:2048
	s_waitcnt vmcnt(0) lgkmcnt(0)
	v_pk_mul_f32 v[4:5], v[8:9], v[4:5]
	v_pk_mul_f32 v[6:7], v[10:11], v[6:7]
	flat_store_dwordx4 v[22:23], v[4:7] offset:2048 sc1
	flat_load_dwordx4 v[4:7], v[18:19] offset:3072
	s_waitcnt vmcnt(0) lgkmcnt(0)
	v_pk_mul_f32 v[0:1], v[4:5], v[0:1]
	v_pk_mul_f32 v[2:3], v[6:7], v[2:3]
	flat_store_dwordx4 v[22:23], v[0:3] offset:3072 sc1
	s_cbranch_scc0 .LBB0_2957
